# attention combine epilogue: 32 serialized ds_read2 pipelined 8 deep through dead Q-fragment registers
# speedup vs baseline: 1.0109x; 1.0109x over previous
; __device__ __forceinline__ float shx(float v, int o, int lane) { return __int_as_float(__builtin_amdgcn_ds_bpermute((lane ^ o) << 2, __float_as_int(v))); }
; __device__ __forceinline__ int crow(int r, int hi) { return (r & 3) + 8 * (r >> 2) + 4 * hi; }
; __device__ __forceinline__ void attn_unit(LAS unsigned char* lds, bf16_t* Zg, const unsigned char* KVg, int S, int b, int h, int qb, const float* lq1, const float* lk1, const float* lq2, const float* lk2, const float* subln_g, const float* rel_bias, bool dostore = true) {
;     ...
;     __syncthreads();
;     if (mp == 0) {
;         float ss[16];
; #pragma unroll
;         for (int r = 0; r < 16; ++r) { float a = 0.f;
; #pragma unroll
;             for (int db = 0; db < 4; ++db) { const float d = o[db][r] * inv[r] - exch[(32 * qsub + crow(r, hi)) * 128 + db * 32 + r32]; o[db][r] = d; a += d * d; }
;             ss[r] = a; }
; #pragma unroll
;         for (int r = 0; r < 16; ++r) {
; #pragma unroll
;             for (int sft = 1; sft < 32; sft <<= 1) ss[r] += shx(ss[r], sft, lane);
;             ss[r] = (1.0f - LAMBDA_INIT) / sqrtf(ss[r] * (1.0f / 128.0f) + EPS); }
.LBB0_287:
	s_cmpk_gt_u32 s15, 0xff
	s_waitcnt lgkmcnt(0)
	s_barrier
	s_cbranch_scc1 .LBB0_187
	v_or_b32_e32 v0, s84, v211
	v_lshlrev_b32_e32 v0, 9, v0
	v_add3_u32 v0, 0, v82, v0
	v_add_u32_e32 v103, 0x400, v0
	v_add_u32_e32 v106, 0x1000, v0
	v_add_u32_e32 v107, 0x1400, v0
	v_add_u32_e32 v108, 0x2000, v0
	v_add_u32_e32 v109, 0x2400, v0
	v_add_u32_e32 v110, 0x3000, v0
	v_add_u32_e32 v111, 0x3400, v0
	ds_read2_b32 v[178:179], v0 offset1:32
	ds_read2_b32 v[180:181], v0 offset0:64 offset1:96
	ds_read2_b32 v[182:183], v0 offset0:128 offset1:160
	ds_read2_b32 v[184:185], v0 offset0:192 offset1:224
	ds_read2_b32 v[186:187], v103 offset1:32
	ds_read2_b32 v[188:189], v103 offset0:64 offset1:96
	ds_read2_b32 v[190:191], v103 offset0:128 offset1:160
	ds_read2_b32 v[192:193], v103 offset0:192 offset1:224
	s_nop 0
	s_nop 0
	s_waitcnt lgkmcnt(7)
	v_fma_f32 v83, v50, v78, -v178
	v_fma_f32 v50, v34, v78, -v179
	ds_read2_b32 v[178:179], v106 offset1:32
	s_nop 0
	v_mul_f32_e32 v102, v50, v50
	v_fmac_f32_e32 v102, v83, v83
	s_nop 0
	s_waitcnt lgkmcnt(7)
	v_fma_f32 v34, v18, v78, -v180
	v_fma_f32 v2, v2, v78, -v181
	ds_read2_b32 v[180:181], v106 offset0:64 offset1:96
	s_nop 0
	v_add_u32_e32 v18, 0x400, v0
	v_fmac_f32_e32 v102, v34, v34
	v_fmac_f32_e32 v102, v2, v2
	s_nop 0
	s_waitcnt lgkmcnt(7)
	v_fma_f32 v78, v51, v79, -v182
	v_fma_f32 v51, v35, v79, -v183
	ds_read2_b32 v[182:183], v106 offset0:128 offset1:160
	s_nop 0
	v_mul_f32_e32 v101, v51, v51
	v_fmac_f32_e32 v101, v78, v78
	s_nop 0
	s_waitcnt lgkmcnt(7)
	v_fma_f32 v35, v19, v79, -v184
	v_fma_f32 v3, v3, v79, -v185
	ds_read2_b32 v[184:185], v106 offset0:192 offset1:224
	s_nop 0
	v_add_u32_e32 v19, 0x1000, v0
	v_fmac_f32_e32 v101, v35, v35
	v_fmac_f32_e32 v101, v3, v3
	s_nop 0
	s_waitcnt lgkmcnt(7)
	v_fma_f32 v79, v52, v80, -v186
	v_fma_f32 v52, v36, v80, -v187
	ds_read2_b32 v[186:187], v107 offset1:32
	s_nop 0
	v_mul_f32_e32 v100, v52, v52
	v_fmac_f32_e32 v100, v79, v79
	s_nop 0
	s_waitcnt lgkmcnt(7)
	v_fma_f32 v36, v20, v80, -v188
	v_fma_f32 v4, v4, v80, -v189
	ds_read2_b32 v[188:189], v107 offset0:64 offset1:96
	s_nop 0
	v_fmac_f32_e32 v100, v36, v36
	v_fmac_f32_e32 v100, v4, v4
	s_nop 0
	s_waitcnt lgkmcnt(7)
	v_fma_f32 v80, v53, v81, -v190
	v_fma_f32 v53, v37, v81, -v191
	ds_read2_b32 v[190:191], v107 offset0:128 offset1:160
	s_nop 0
	v_mul_f32_e32 v99, v53, v53
	v_fmac_f32_e32 v99, v80, v80
	s_nop 0
	s_waitcnt lgkmcnt(7)
	v_fma_f32 v37, v21, v81, -v192
	s_nop 0
	v_fma_f32 v5, v5, v81, -v193
	ds_read2_b32 v[192:193], v107 offset0:192 offset1:224
	v_fmac_f32_e32 v99, v37, v37
	v_fmac_f32_e32 v99, v5, v5
	s_nop 0
	s_waitcnt lgkmcnt(7)
	v_fma_f32 v81, v54, v74, -v178
	v_fma_f32 v54, v38, v74, -v179
	ds_read2_b32 v[178:179], v108 offset1:32
	s_nop 0
	v_mul_f32_e32 v98, v54, v54
	v_fmac_f32_e32 v98, v81, v81
	s_nop 0
	s_waitcnt lgkmcnt(7)
	v_fma_f32 v38, v22, v74, -v180
	v_fma_f32 v6, v6, v74, -v181
	ds_read2_b32 v[180:181], v108 offset0:64 offset1:96
	s_nop 0
	v_fmac_f32_e32 v98, v38, v38
	v_fmac_f32_e32 v98, v6, v6
	s_nop 0
	s_waitcnt lgkmcnt(7)
	v_fma_f32 v74, v55, v75, -v182
	v_fma_f32 v55, v39, v75, -v183
	ds_read2_b32 v[182:183], v108 offset0:128 offset1:160
	s_nop 0
	v_mul_f32_e32 v97, v55, v55
	v_fmac_f32_e32 v97, v74, v74
	s_nop 0
	s_waitcnt lgkmcnt(7)
	v_fma_f32 v39, v23, v75, -v184
	v_add_u32_e32 v20, 0x1400, v0
	s_nop 0
	v_fma_f32 v7, v7, v75, -v185
	ds_read2_b32 v[184:185], v108 offset0:192 offset1:224
	v_add_u32_e32 v21, 0x2000, v0
	v_fmac_f32_e32 v97, v39, v39
	v_fmac_f32_e32 v97, v7, v7
	s_nop 0
	s_waitcnt lgkmcnt(7)
	v_fma_f32 v75, v56, v76, -v186
	v_fma_f32 v56, v40, v76, -v187
	ds_read2_b32 v[186:187], v109 offset1:32
	s_nop 0
	v_mul_f32_e32 v96, v56, v56
	v_fmac_f32_e32 v96, v75, v75
	s_nop 0
	s_waitcnt lgkmcnt(7)
	v_fma_f32 v40, v24, v76, -v188
	v_fma_f32 v8, v8, v76, -v189
	ds_read2_b32 v[188:189], v109 offset0:64 offset1:96
	s_nop 0
	v_fmac_f32_e32 v96, v40, v40
	v_fmac_f32_e32 v96, v8, v8
	s_nop 0
	s_waitcnt lgkmcnt(7)
	v_fma_f32 v76, v57, v77, -v190
	v_fma_f32 v57, v41, v77, -v191
	ds_read2_b32 v[190:191], v109 offset0:128 offset1:160
	s_nop 0
	v_mul_f32_e32 v95, v57, v57
	v_fmac_f32_e32 v95, v76, v76
	s_nop 0
	s_waitcnt lgkmcnt(7)
	v_fma_f32 v25, v25, v77, -v192
	v_fma_f32 v9, v9, v77, -v193
	ds_read2_b32 v[192:193], v109 offset0:192 offset1:224
	s_nop 0
	v_fmac_f32_e32 v95, v25, v25
	v_fmac_f32_e32 v95, v9, v9
	s_nop 0
	s_waitcnt lgkmcnt(7)
	v_fma_f32 v77, v58, v70, -v178
	v_fma_f32 v58, v42, v70, -v179
	ds_read2_b32 v[178:179], v110 offset0:64 offset1:96
	s_nop 0
	v_mul_f32_e32 v90, v58, v58
	v_fmac_f32_e32 v90, v77, v77
	s_nop 0
	s_waitcnt lgkmcnt(7)
	v_fma_f32 v26, v26, v70, -v180
	v_fma_f32 v10, v10, v70, -v181
	ds_read2_b32 v[180:181], v110 offset1:32
	s_nop 0
	v_fmac_f32_e32 v90, v26, v26
	v_fmac_f32_e32 v90, v10, v10
	s_nop 0
	s_waitcnt lgkmcnt(7)
	v_fma_f32 v70, v59, v71, -v182
	v_fma_f32 v43, v43, v71, -v183
	ds_read2_b32 v[182:183], v110 offset0:128 offset1:160
	s_nop 0
	v_mul_f32_e32 v93, v43, v43
	v_fmac_f32_e32 v93, v70, v70
	s_nop 0
	s_waitcnt lgkmcnt(7)
	v_fma_f32 v41, v27, v71, -v184
	v_add_u32_e32 v22, 0x2400, v0
	s_nop 0
	v_fma_f32 v11, v11, v71, -v185
	ds_read2_b32 v[184:185], v110 offset0:192 offset1:224
	v_add_u32_e32 v23, 0x3000, v0
	s_nop 1
	v_mov_b32_dpp v27, v102 quad_perm:[1,0,3,2] row_mask:0xf bank_mask:0xf
	v_fmac_f32_e32 v93, v41, v41
	s_nop 0
	s_waitcnt lgkmcnt(7)
	v_fma_f32 v71, v60, v72, -v186
	v_fma_f32 v59, v44, v72, -v187
	ds_read2_b32 v[186:187], v111 offset1:32
	s_nop 0
	s_nop 0
	v_add_f32_e32 v27, v102, v27
	v_fmac_f32_e32 v93, v11, v11
	v_mul_f32_e32 v94, v59, v59
	v_fmac_f32_e32 v94, v71, v71
	s_nop 0
	s_waitcnt lgkmcnt(7)
; __device__ __forceinline__ float shx(float v, int o, int lane) { return __int_as_float(__builtin_amdgcn_ds_bpermute((lane ^ o) << 2, __float_as_int(v))); }
; __device__ __forceinline__ int crow(int r, int hi) { return (r & 3) + 8 * (r >> 2) + 4 * hi; }
; __device__ __forceinline__ void attn_unit(LAS unsigned char* lds, bf16_t* Zg, const unsigned char* KVg, int S, int b, int h, int qb, const float* lq1, const float* lk1, const float* lq2, const float* lk2, const float* subln_g, const float* rel_bias, bool dostore = true) {
;     ...
;         for (int r = 0; r < 16; ++r) { float a = 0.f;
; #pragma unroll
;             for (int db = 0; db < 4; ++db) { const float d = o[db][r] * inv[r] - exch[(32 * qsub + crow(r, hi)) * 128 + db * 32 + r32]; o[db][r] = d; a += d * d; }
;             ss[r] = a; }
; #pragma unroll
;         for (int r = 0; r < 16; ++r) {
; #pragma unroll
;             for (int sft = 1; sft < 32; sft <<= 1) ss[r] += shx(ss[r], sft, lane);
;             ss[r] = (1.0f - LAMBDA_INIT) / sqrtf(ss[r] * (1.0f / 128.0f) + EPS); }
; #pragma unroll
;         for (int db = 0; db < 4; ++db) { const float sg = subln_g[db * 32 + r32];
; #pragma unroll
;             for (int r = 0; r < 16; ++r) exch[(32 * qsub + crow(r, hi)) * 128 + db * 32 + r32] = o[db][r] * ss[r] * sg; }
	v_fma_f32 v28, v28, v72, -v188
	v_fma_f32 v12, v12, v72, -v189
	ds_read2_b32 v[188:189], v111 offset0:64 offset1:96
	s_nop 0
	v_fmac_f32_e32 v94, v28, v28
	v_fmac_f32_e32 v94, v12, v12
	s_nop 0
	s_waitcnt lgkmcnt(7)
	v_fma_f32 v61, v61, v73, -v190
	v_fma_f32 v45, v45, v73, -v191
	ds_read2_b32 v[190:191], v111 offset0:128 offset1:160
	s_nop 0
	v_mul_f32_e32 v92, v45, v45
	v_fmac_f32_e32 v92, v61, v61
	s_nop 0
	s_waitcnt lgkmcnt(7)
	v_fma_f32 v29, v29, v73, -v192
	v_fma_f32 v13, v13, v73, -v193
	ds_read2_b32 v[192:193], v111 offset0:192 offset1:224
	s_nop 0
	s_nop 0
	v_fmac_f32_e32 v92, v29, v29
	v_fmac_f32_e32 v92, v13, v13
	s_nop 0
	s_waitcnt lgkmcnt(7)
	v_fma_f32 v42, v30, v66, -v178
	s_nop 1
	v_mov_b32_dpp v30, v27 quad_perm:[2,3,0,1] row_mask:0xf bank_mask:0xf
	v_fma_f32 v14, v14, v66, -v179
	s_nop 0
	s_nop 0
	s_waitcnt lgkmcnt(6)
	v_fma_f32 v72, v62, v66, -v180
	v_fma_f32 v46, v46, v66, -v181
	s_nop 0
	v_add_f32_e32 v27, v27, v30
	s_nop 1
	v_mov_b32_dpp v30, v27 row_half_mirror row_mask:0xf bank_mask:0xf
	s_nop 0
	s_waitcnt lgkmcnt(5)
	v_fma_f32 v63, v63, v67, -v182
	v_fma_f32 v60, v47, v67, -v183
	s_nop 0
	v_mul_f32_e32 v91, v46, v46
	s_nop 0
	v_add_f32_e32 v27, v27, v30
	s_nop 1
	v_mov_b32_dpp v30, v27 row_ror:8 row_mask:0xf bank_mask:0xf
	v_fmac_f32_e32 v91, v72, v72
	s_nop 0
	s_waitcnt lgkmcnt(4)
	v_fma_f32 v24, v15, v67, -v185
	v_add_u32_e32 v15, 0x3400, v0
	v_fma_f32 v31, v31, v67, -v184
	s_nop 0
	v_add_f32_e32 v27, v27, v30
	v_mov_b32_e32 v30, v27
	s_nop 1
	v_permlane16_swap_b32_e32 v30, v27
	s_nop 0
	v_fmac_f32_e32 v91, v42, v42
	v_fmac_f32_e32 v91, v14, v14
	v_mul_f32_e32 v89, v60, v60
	s_nop 0
	v_add_f32_e32 v27, v27, v30
	v_fmamk_f32 v27, v27, 0x3c000000, v206
	v_cmp_gt_f32_e32 vcc, s36, v27
	v_mul_f32_e32 v30, 0x4f800000, v27
	s_nop 0
	s_waitcnt lgkmcnt(3)
	v_fma_f32 v64, v64, v68, -v186
	v_cndmask_b32_e32 v27, v27, v30, vcc
	v_sqrt_f32_e32 v30, v27
	v_fma_f32 v48, v48, v68, -v187
	s_nop 0
	v_fmac_f32_e32 v89, v63, v63
	v_add_u32_e32 v44, -1, v30
	v_fma_f32 v47, -v44, v30, v27
	v_cmp_ge_f32_e64 s[4:5], 0, v47
	v_add_u32_e32 v47, 1, v30
	s_nop 0
	s_waitcnt lgkmcnt(2)
	v_fma_f32 v32, v32, v68, -v188
	v_cndmask_b32_e64 v44, v30, v44, s[4:5]
	v_fma_f32 v30, -v47, v30, v27
	v_cmp_lt_f32_e64 s[4:5], 0, v30
	v_fma_f32 v16, v16, v68, -v189
	s_nop 0
	v_cndmask_b32_e64 v30, v44, v47, s[4:5]
	v_mul_f32_e32 v44, 0x37800000, v30
	v_cndmask_b32_e32 v30, v30, v44, vcc
	v_cmp_class_f32_e32 vcc, v27, v205
	s_nop 0
	s_waitcnt lgkmcnt(1)
	v_fma_f32 v65, v65, v69, -v190
	v_fma_f32 v49, v49, v69, -v191
	v_cndmask_b32_e32 v27, v30, v27, vcc
	v_div_scale_f32 v30, s[4:5], v27, v27, s95
	v_rcp_f32_e32 v44, v30
	s_nop 0
	v_fmac_f32_e32 v89, v31, v31
	v_fmac_f32_e32 v89, v24, v24
	v_fma_f32 v47, -v30, v44, 1.0
	v_fmac_f32_e32 v44, v47, v44
	v_div_scale_f32 v47, vcc, s95, v27, s95
	v_mul_f32_e32 v62, v47, v44
	s_nop 0
	s_waitcnt lgkmcnt(0)
	v_fma_f32 v33, v33, v69, -v192
	v_fma_f32 v66, -v30, v62, v47
	v_fmac_f32_e32 v62, v66, v44
	v_fma_f32 v30, -v30, v62, v47
	v_div_fmas_f32 v30, v30, v44, v62
	v_div_fixup_f32 v27, v30, v27, s95
	s_nop 1
	v_mov_b32_dpp v30, v101 quad_perm:[1,0,3,2] row_mask:0xf bank_mask:0xf
	v_fma_f32 v17, v17, v69, -v193
	v_mul_f32_e32 v73, v48, v48
	v_fmac_f32_e32 v73, v64, v64
	v_fmac_f32_e32 v73, v32, v32
	s_nop 0
	v_add_f32_e32 v30, v101, v30
	s_nop 1
	v_mov_b32_dpp v44, v30 quad_perm:[2,3,0,1] row_mask:0xf bank_mask:0xf
	v_fmac_f32_e32 v73, v16, v16
	v_mul_f32_e32 v68, v49, v49
	v_fmac_f32_e32 v68, v65, v65
	v_fmac_f32_e32 v68, v33, v33
	s_nop 0
	v_add_f32_e32 v30, v30, v44
	s_nop 1
	v_mov_b32_dpp v44, v30 row_half_mirror row_mask:0xf bank_mask:0xf
	v_fmac_f32_e32 v68, v17, v17
	v_mul_f32_e32 v83, v83, v27
	v_mul_f32_e32 v50, v50, v27
	v_mul_f32_e32 v34, v34, v27
	s_nop 0
	v_add_f32_e32 v30, v30, v44
	s_nop 1
	v_mov_b32_dpp v44, v30 row_ror:8 row_mask:0xf bank_mask:0xf
	v_mul_f32_e32 v2, v2, v27
	s_nop 0
	v_add_f32_e32 v30, v30, v44
	v_mov_b32_e32 v44, v30
	s_nop 1
	v_permlane16_swap_b32_e32 v44, v30
	s_nop 0
	v_add_f32_e32 v30, v30, v44
	v_fmamk_f32 v30, v30, 0x3c000000, v206
	v_cmp_gt_f32_e32 vcc, s36, v30
	v_mul_f32_e32 v44, 0x4f800000, v30
	s_nop 0
	v_cndmask_b32_e32 v30, v30, v44, vcc
	v_sqrt_f32_e32 v44, v30
	s_nop 0
	v_add_u32_e32 v47, -1, v44
	v_fma_f32 v62, -v47, v44, v30
	v_cmp_ge_f32_e64 s[4:5], 0, v62
	v_add_u32_e32 v62, 1, v44
	s_nop 0
	v_cndmask_b32_e64 v47, v44, v47, s[4:5]
	v_fma_f32 v44, -v62, v44, v30
	v_cmp_lt_f32_e64 s[4:5], 0, v44
	s_nop 1
	v_cndmask_b32_e64 v44, v47, v62, s[4:5]
	v_mul_f32_e32 v47, 0x37800000, v44
	v_cndmask_b32_e32 v44, v44, v47, vcc
	v_cmp_class_f32_e32 vcc, v30, v205
	s_nop 1
	v_cndmask_b32_e32 v30, v44, v30, vcc
	v_div_scale_f32 v44, s[4:5], v30, v30, s95
	v_rcp_f32_e32 v47, v44
	s_nop 0
	v_fma_f32 v62, -v44, v47, 1.0
	v_fmac_f32_e32 v47, v62, v47
	v_div_scale_f32 v62, vcc, s95, v30, s95
	v_mul_f32_e32 v66, v62, v47
	v_fma_f32 v67, -v44, v66, v62
	v_fmac_f32_e32 v66, v67, v47
	v_fma_f32 v44, -v44, v66, v62
	v_div_fmas_f32 v44, v44, v47, v66
	v_div_fixup_f32 v30, v44, v30, s95
	s_nop 1
	v_mov_b32_dpp v44, v100 quad_perm:[1,0,3,2] row_mask:0xf bank_mask:0xf
	v_mul_f32_e32 v78, v78, v30
	s_nop 0
	v_add_f32_e32 v44, v100, v44
	s_nop 1
	v_mov_b32_dpp v47, v44 quad_perm:[2,3,0,1] row_mask:0xf bank_mask:0xf
	s_nop 0
	v_add_f32_e32 v44, v44, v47
	s_nop 1
	v_mov_b32_dpp v47, v44 row_half_mirror row_mask:0xf bank_mask:0xf
	s_nop 0
	v_add_f32_e32 v44, v44, v47
	s_nop 1
	v_mov_b32_dpp v47, v44 row_ror:8 row_mask:0xf bank_mask:0xf
	s_nop 0
	v_add_f32_e32 v44, v44, v47
	v_mov_b32_e32 v47, v44
	s_nop 1
	v_permlane16_swap_b32_e32 v47, v44
	s_nop 0
	v_add_f32_e32 v44, v44, v47
; __device__ __forceinline__ float shx(float v, int o, int lane) { return __int_as_float(__builtin_amdgcn_ds_bpermute((lane ^ o) << 2, __float_as_int(v))); }
; __device__ __forceinline__ int crow(int r, int hi) { return (r & 3) + 8 * (r >> 2) + 4 * hi; }
; __device__ __forceinline__ void attn_unit(LAS unsigned char* lds, bf16_t* Zg, const unsigned char* KVg, int S, int b, int h, int qb, const float* lq1, const float* lk1, const float* lq2, const float* lk2, const float* subln_g, const float* rel_bias, bool dostore = true) {
;     ...
;         for (int r = 0; r < 16; ++r) {
; #pragma unroll
;             for (int sft = 1; sft < 32; sft <<= 1) ss[r] += shx(ss[r], sft, lane);
;             ss[r] = (1.0f - LAMBDA_INIT) / sqrtf(ss[r] * (1.0f / 128.0f) + EPS); }
; #pragma unroll
;         for (int db = 0; db < 4; ++db) { const float sg = subln_g[db * 32 + r32];
; #pragma unroll
;             for (int r = 0; r < 16; ++r) exch[(32 * qsub + crow(r, hi)) * 128 + db * 32 + r32] = o[db][r] * ss[r] * sg; }
	v_fmamk_f32 v44, v44, 0x3c000000, v206
	v_cmp_gt_f32_e32 vcc, s36, v44
	v_mul_f32_e32 v47, 0x4f800000, v44
	s_nop 0
	v_cndmask_b32_e32 v44, v44, v47, vcc
	v_sqrt_f32_e32 v47, v44
	s_nop 0
	v_add_u32_e32 v62, -1, v47
	v_fma_f32 v66, -v62, v47, v44
	v_cmp_ge_f32_e64 s[4:5], 0, v66
	v_add_u32_e32 v66, 1, v47
	s_nop 0
	v_cndmask_b32_e64 v62, v47, v62, s[4:5]
	v_fma_f32 v47, -v66, v47, v44
	v_cmp_lt_f32_e64 s[4:5], 0, v47
	s_nop 1
	v_cndmask_b32_e64 v47, v62, v66, s[4:5]
	v_mul_f32_e32 v62, 0x37800000, v47
	v_cndmask_b32_e32 v47, v47, v62, vcc
	v_cmp_class_f32_e32 vcc, v44, v205
	s_nop 1
	v_cndmask_b32_e32 v44, v47, v44, vcc
	v_div_scale_f32 v47, s[4:5], v44, v44, s95
	v_rcp_f32_e32 v62, v47
	s_nop 0
	v_fma_f32 v66, -v47, v62, 1.0
	v_fmac_f32_e32 v62, v66, v62
	v_div_scale_f32 v66, vcc, s95, v44, s95
	v_mul_f32_e32 v67, v66, v62
	v_fma_f32 v69, -v47, v67, v66
	v_fmac_f32_e32 v67, v69, v62
	v_fma_f32 v47, -v47, v67, v66
	v_div_fmas_f32 v47, v47, v62, v67
	v_div_fixup_f32 v44, v47, v44, s95
	s_nop 1
	v_mov_b32_dpp v47, v99 quad_perm:[1,0,3,2] row_mask:0xf bank_mask:0xf
	v_mul_f32_e32 v79, v79, v44
	s_nop 0
	v_add_f32_e32 v47, v99, v47
	s_nop 1
	v_mov_b32_dpp v62, v47 quad_perm:[2,3,0,1] row_mask:0xf bank_mask:0xf
	s_nop 0
	v_add_f32_e32 v47, v47, v62
	s_nop 1
	v_mov_b32_dpp v62, v47 row_half_mirror row_mask:0xf bank_mask:0xf
	s_nop 0
	v_add_f32_e32 v47, v47, v62
	s_nop 1
	v_mov_b32_dpp v62, v47 row_ror:8 row_mask:0xf bank_mask:0xf
	s_nop 0
	v_add_f32_e32 v47, v47, v62
	v_mov_b32_e32 v62, v47
	s_nop 1
	v_permlane16_swap_b32_e32 v62, v47
	s_nop 0
	v_add_f32_e32 v47, v47, v62
	v_fmamk_f32 v47, v47, 0x3c000000, v206
	v_cmp_gt_f32_e32 vcc, s36, v47
	v_mul_f32_e32 v62, 0x4f800000, v47
	s_nop 0
	v_cndmask_b32_e32 v47, v47, v62, vcc
	v_sqrt_f32_e32 v62, v47
	s_nop 0
	v_add_u32_e32 v66, -1, v62
	v_fma_f32 v67, -v66, v62, v47
	v_cmp_ge_f32_e64 s[4:5], 0, v67
	v_add_u32_e32 v67, 1, v62
	s_nop 0
	v_cndmask_b32_e64 v66, v62, v66, s[4:5]
	v_fma_f32 v62, -v67, v62, v47
	v_cmp_lt_f32_e64 s[4:5], 0, v62
	s_nop 1
	v_cndmask_b32_e64 v62, v66, v67, s[4:5]
	v_mul_f32_e32 v66, 0x37800000, v62
	v_cndmask_b32_e32 v62, v62, v66, vcc
	v_cmp_class_f32_e32 vcc, v47, v205
	s_nop 1
	v_cndmask_b32_e32 v47, v62, v47, vcc
	v_div_scale_f32 v62, s[4:5], v47, v47, s95
	v_rcp_f32_e32 v66, v62
	s_nop 0
	v_fma_f32 v67, -v62, v66, 1.0
	v_fmac_f32_e32 v66, v67, v66
	v_div_scale_f32 v67, vcc, s95, v47, s95
	v_mul_f32_e32 v69, v67, v66
	v_fma_f32 v99, -v62, v69, v67
	v_fmac_f32_e32 v69, v99, v66
	v_fma_f32 v62, -v62, v69, v67
	v_div_fmas_f32 v62, v62, v66, v69
	v_div_fixup_f32 v47, v62, v47, s95
	s_nop 1
	v_mov_b32_dpp v62, v98 quad_perm:[1,0,3,2] row_mask:0xf bank_mask:0xf
	v_mul_f32_e32 v80, v80, v47
	s_nop 0
	v_add_f32_e32 v62, v98, v62
	s_nop 1
	v_mov_b32_dpp v66, v62 quad_perm:[2,3,0,1] row_mask:0xf bank_mask:0xf
	s_nop 0
	v_add_f32_e32 v62, v62, v66
	s_nop 1
	v_mov_b32_dpp v66, v62 row_half_mirror row_mask:0xf bank_mask:0xf
	s_nop 0
	v_add_f32_e32 v62, v62, v66
	s_nop 1
	v_mov_b32_dpp v66, v62 row_ror:8 row_mask:0xf bank_mask:0xf
	s_nop 0
	v_add_f32_e32 v62, v62, v66
	v_mov_b32_e32 v66, v62
	s_nop 1
	v_permlane16_swap_b32_e32 v66, v62
	s_nop 0
	v_add_f32_e32 v62, v62, v66
	v_fmamk_f32 v62, v62, 0x3c000000, v206
	v_cmp_gt_f32_e32 vcc, s36, v62
	v_mul_f32_e32 v66, 0x4f800000, v62
	s_nop 0
	v_cndmask_b32_e32 v62, v62, v66, vcc
	v_sqrt_f32_e32 v66, v62
	s_nop 0
	v_add_u32_e32 v67, -1, v66
	v_fma_f32 v69, -v67, v66, v62
	v_cmp_ge_f32_e64 s[4:5], 0, v69
	v_add_u32_e32 v69, 1, v66
	s_nop 0
	v_cndmask_b32_e64 v67, v66, v67, s[4:5]
	v_fma_f32 v66, -v69, v66, v62
	v_cmp_lt_f32_e64 s[4:5], 0, v66
	s_nop 1
	v_cndmask_b32_e64 v66, v67, v69, s[4:5]
	v_mul_f32_e32 v67, 0x37800000, v66
	v_cndmask_b32_e32 v66, v66, v67, vcc
	v_cmp_class_f32_e32 vcc, v62, v205
	s_nop 1
	v_cndmask_b32_e32 v62, v66, v62, vcc
	v_div_scale_f32 v66, s[4:5], v62, v62, s95
	v_rcp_f32_e32 v67, v66
	s_nop 0
	v_fma_f32 v69, -v66, v67, 1.0
	v_fmac_f32_e32 v67, v69, v67
	v_div_scale_f32 v69, vcc, s95, v62, s95
	v_mul_f32_e32 v98, v69, v67
	v_fma_f32 v99, -v66, v98, v69
	v_fmac_f32_e32 v98, v99, v67
	v_fma_f32 v66, -v66, v98, v69
	v_div_fmas_f32 v66, v66, v67, v98
	v_div_fixup_f32 v62, v66, v62, s95
	s_nop 1
	v_mov_b32_dpp v66, v97 quad_perm:[1,0,3,2] row_mask:0xf bank_mask:0xf
	v_mul_f32_e32 v81, v81, v62
	s_nop 0
	v_add_f32_e32 v66, v97, v66
	s_nop 1
	v_mov_b32_dpp v67, v66 quad_perm:[2,3,0,1] row_mask:0xf bank_mask:0xf
	s_nop 0
	v_add_f32_e32 v66, v66, v67
	s_nop 1
	v_mov_b32_dpp v67, v66 row_half_mirror row_mask:0xf bank_mask:0xf
	s_nop 0
	v_add_f32_e32 v66, v66, v67
	s_nop 1
	v_mov_b32_dpp v67, v66 row_ror:8 row_mask:0xf bank_mask:0xf
	s_nop 0
	v_add_f32_e32 v66, v66, v67
	v_mov_b32_e32 v67, v66
	s_nop 1
	v_permlane16_swap_b32_e32 v67, v66
	s_nop 0
	v_add_f32_e32 v66, v66, v67
	v_fmamk_f32 v66, v66, 0x3c000000, v206
	v_cmp_gt_f32_e32 vcc, s36, v66
	v_mul_f32_e32 v67, 0x4f800000, v66
	s_nop 0
	v_cndmask_b32_e32 v66, v66, v67, vcc
	v_sqrt_f32_e32 v67, v66
	s_nop 0
	v_add_u32_e32 v69, -1, v67
	v_fma_f32 v97, -v69, v67, v66
	v_cmp_ge_f32_e64 s[4:5], 0, v97
	v_add_u32_e32 v97, 1, v67
	s_nop 0
	v_cndmask_b32_e64 v69, v67, v69, s[4:5]
	v_fma_f32 v67, -v97, v67, v66
	v_cmp_lt_f32_e64 s[4:5], 0, v67
	s_nop 1
	v_cndmask_b32_e64 v67, v69, v97, s[4:5]
	v_mul_f32_e32 v69, 0x37800000, v67
	v_cndmask_b32_e32 v67, v67, v69, vcc
	v_cmp_class_f32_e32 vcc, v66, v205
	s_nop 1
	v_cndmask_b32_e32 v66, v67, v66, vcc
	v_div_scale_f32 v67, s[4:5], v66, v66, s95
	v_rcp_f32_e32 v69, v67
	s_nop 0
	v_fma_f32 v97, -v67, v69, 1.0
	v_fmac_f32_e32 v69, v97, v69
	v_div_scale_f32 v97, vcc, s95, v66, s95
	v_mul_f32_e32 v98, v97, v69
	v_fma_f32 v99, -v67, v98, v97
; __device__ __forceinline__ float shx(float v, int o, int lane) { return __int_as_float(__builtin_amdgcn_ds_bpermute((lane ^ o) << 2, __float_as_int(v))); }
; __device__ __forceinline__ int crow(int r, int hi) { return (r & 3) + 8 * (r >> 2) + 4 * hi; }
; __device__ __forceinline__ void attn_unit(LAS unsigned char* lds, bf16_t* Zg, const unsigned char* KVg, int S, int b, int h, int qb, const float* lq1, const float* lk1, const float* lq2, const float* lk2, const float* subln_g, const float* rel_bias, bool dostore = true) {
;     ...
;         for (int r = 0; r < 16; ++r) {
; #pragma unroll
;             for (int sft = 1; sft < 32; sft <<= 1) ss[r] += shx(ss[r], sft, lane);
;             ss[r] = (1.0f - LAMBDA_INIT) / sqrtf(ss[r] * (1.0f / 128.0f) + EPS); }
; #pragma unroll
;         for (int db = 0; db < 4; ++db) { const float sg = subln_g[db * 32 + r32];
; #pragma unroll
;             for (int r = 0; r < 16; ++r) exch[(32 * qsub + crow(r, hi)) * 128 + db * 32 + r32] = o[db][r] * ss[r] * sg; }
	v_fmac_f32_e32 v98, v99, v69
	v_fma_f32 v67, -v67, v98, v97
	v_div_fmas_f32 v67, v67, v69, v98
	v_div_fixup_f32 v66, v67, v66, s95
	s_nop 1
	v_mov_b32_dpp v67, v96 quad_perm:[1,0,3,2] row_mask:0xf bank_mask:0xf
	v_mul_f32_e32 v74, v74, v66
	s_nop 0
	v_add_f32_e32 v67, v96, v67
	s_nop 1
	v_mov_b32_dpp v69, v67 quad_perm:[2,3,0,1] row_mask:0xf bank_mask:0xf
	s_nop 0
	v_add_f32_e32 v67, v67, v69
	s_nop 1
	v_mov_b32_dpp v69, v67 row_half_mirror row_mask:0xf bank_mask:0xf
	s_nop 0
	v_add_f32_e32 v67, v67, v69
	s_nop 1
	v_mov_b32_dpp v69, v67 row_ror:8 row_mask:0xf bank_mask:0xf
	s_nop 0
	v_add_f32_e32 v67, v67, v69
	v_mov_b32_e32 v69, v67
	s_nop 1
	v_permlane16_swap_b32_e32 v69, v67
	s_nop 0
	v_add_f32_e32 v67, v67, v69
	v_fmamk_f32 v67, v67, 0x3c000000, v206
	v_cmp_gt_f32_e32 vcc, s36, v67
	v_mul_f32_e32 v69, 0x4f800000, v67
	s_nop 0
	v_cndmask_b32_e32 v67, v67, v69, vcc
	v_sqrt_f32_e32 v69, v67
	s_nop 0
	v_add_u32_e32 v96, -1, v69
	v_fma_f32 v97, -v96, v69, v67
	v_cmp_ge_f32_e64 s[4:5], 0, v97
	v_add_u32_e32 v97, 1, v69
	s_nop 0
	v_cndmask_b32_e64 v96, v69, v96, s[4:5]
	v_fma_f32 v69, -v97, v69, v67
	v_cmp_lt_f32_e64 s[4:5], 0, v69
	s_nop 1
	v_cndmask_b32_e64 v69, v96, v97, s[4:5]
	v_mul_f32_e32 v96, 0x37800000, v69
	v_cndmask_b32_e32 v69, v69, v96, vcc
	v_cmp_class_f32_e32 vcc, v67, v205
	s_nop 1
	v_cndmask_b32_e32 v67, v69, v67, vcc
	v_div_scale_f32 v69, s[4:5], v67, v67, s95
	v_rcp_f32_e32 v96, v69
	s_nop 0
	v_fma_f32 v97, -v69, v96, 1.0
	v_fmac_f32_e32 v96, v97, v96
	v_div_scale_f32 v97, vcc, s95, v67, s95
	v_mul_f32_e32 v98, v97, v96
	v_fma_f32 v99, -v69, v98, v97
	v_fmac_f32_e32 v98, v99, v96
	v_fma_f32 v69, -v69, v98, v97
	v_div_fmas_f32 v69, v69, v96, v98
	v_div_fixup_f32 v67, v69, v67, s95
	s_nop 1
	v_mov_b32_dpp v69, v95 quad_perm:[1,0,3,2] row_mask:0xf bank_mask:0xf
	v_mul_f32_e32 v75, v75, v67
	s_nop 0
	v_add_f32_e32 v69, v95, v69
	s_nop 1
	v_mov_b32_dpp v95, v69 quad_perm:[2,3,0,1] row_mask:0xf bank_mask:0xf
	s_nop 0
	v_add_f32_e32 v69, v69, v95
	s_nop 1
	v_mov_b32_dpp v95, v69 row_half_mirror row_mask:0xf bank_mask:0xf
	s_nop 0
	v_add_f32_e32 v69, v69, v95
	s_nop 1
	v_mov_b32_dpp v95, v69 row_ror:8 row_mask:0xf bank_mask:0xf
	s_nop 0
	v_add_f32_e32 v69, v69, v95
	v_mov_b32_e32 v95, v69
	s_nop 1
	v_permlane16_swap_b32_e32 v95, v69
	s_nop 0
	v_add_f32_e32 v69, v69, v95
	v_fmamk_f32 v69, v69, 0x3c000000, v206
	v_cmp_gt_f32_e32 vcc, s36, v69
	v_mul_f32_e32 v95, 0x4f800000, v69
	s_nop 0
	v_cndmask_b32_e32 v69, v69, v95, vcc
	v_sqrt_f32_e32 v95, v69
	s_nop 0
	v_add_u32_e32 v96, -1, v95
	v_fma_f32 v97, -v96, v95, v69
	v_cmp_ge_f32_e64 s[4:5], 0, v97
	v_add_u32_e32 v97, 1, v95
	s_nop 0
	v_cndmask_b32_e64 v96, v95, v96, s[4:5]
	v_fma_f32 v95, -v97, v95, v69
	v_cmp_lt_f32_e64 s[4:5], 0, v95
	s_nop 1
	v_cndmask_b32_e64 v95, v96, v97, s[4:5]
	v_mul_f32_e32 v96, 0x37800000, v95
	v_cndmask_b32_e32 v95, v95, v96, vcc
	v_cmp_class_f32_e32 vcc, v69, v205
	s_nop 1
	v_cndmask_b32_e32 v69, v95, v69, vcc
	v_div_scale_f32 v95, s[4:5], v69, v69, s95
	v_rcp_f32_e32 v96, v95
	s_nop 0
	v_fma_f32 v97, -v95, v96, 1.0
	v_fmac_f32_e32 v96, v97, v96
	v_div_scale_f32 v97, vcc, s95, v69, s95
	v_mul_f32_e32 v98, v97, v96
	v_fma_f32 v99, -v95, v98, v97
	v_fmac_f32_e32 v98, v99, v96
	v_fma_f32 v95, -v95, v98, v97
	v_div_fmas_f32 v95, v95, v96, v98
	v_div_fixup_f32 v69, v95, v69, s95
	s_nop 1
	v_mov_b32_dpp v95, v90 quad_perm:[1,0,3,2] row_mask:0xf bank_mask:0xf
	v_mul_f32_e32 v76, v76, v69
	v_mul_f32_e32 v25, v25, v69
	s_nop 0
	v_add_f32_e32 v90, v90, v95
	s_nop 1
	v_mov_b32_dpp v95, v90 quad_perm:[2,3,0,1] row_mask:0xf bank_mask:0xf
	s_nop 0
	v_add_f32_e32 v90, v90, v95
	s_nop 1
	v_mov_b32_dpp v95, v90 row_half_mirror row_mask:0xf bank_mask:0xf
	s_nop 0
	v_add_f32_e32 v90, v90, v95
	s_nop 1
	v_mov_b32_dpp v95, v90 row_ror:8 row_mask:0xf bank_mask:0xf
	s_nop 0
	v_add_f32_e32 v90, v90, v95
	v_mov_b32_e32 v95, v90
	s_nop 1
	v_permlane16_swap_b32_e32 v95, v90
	s_nop 0
	v_add_f32_e32 v90, v90, v95
	v_fmamk_f32 v90, v90, 0x3c000000, v206
	v_cmp_gt_f32_e32 vcc, s36, v90
	v_mul_f32_e32 v95, 0x4f800000, v90
	s_nop 0
	v_cndmask_b32_e32 v90, v90, v95, vcc
	v_sqrt_f32_e32 v95, v90
	s_nop 0
	v_add_u32_e32 v96, -1, v95
	v_fma_f32 v97, -v96, v95, v90
	v_cmp_ge_f32_e64 s[4:5], 0, v97
	v_add_u32_e32 v97, 1, v95
	s_nop 0
	v_cndmask_b32_e64 v96, v95, v96, s[4:5]
	v_fma_f32 v95, -v97, v95, v90
	v_cmp_lt_f32_e64 s[4:5], 0, v95
	s_nop 1
	v_cndmask_b32_e64 v95, v96, v97, s[4:5]
	v_mul_f32_e32 v96, 0x37800000, v95
	v_cndmask_b32_e32 v95, v95, v96, vcc
	v_cmp_class_f32_e32 vcc, v90, v205
	s_nop 1
	v_cndmask_b32_e32 v90, v95, v90, vcc
	v_div_scale_f32 v95, s[4:5], v90, v90, s95
	v_rcp_f32_e32 v96, v95
	s_nop 0
	v_fma_f32 v97, -v95, v96, 1.0
	v_fmac_f32_e32 v96, v97, v96
	v_div_scale_f32 v97, vcc, s95, v90, s95
	v_mul_f32_e32 v98, v97, v96
	v_fma_f32 v99, -v95, v98, v97
	v_fmac_f32_e32 v98, v99, v96
	v_fma_f32 v95, -v95, v98, v97
	v_div_fmas_f32 v95, v95, v96, v98
	v_div_fixup_f32 v90, v95, v90, s95
	s_nop 1
	v_mov_b32_dpp v95, v93 quad_perm:[1,0,3,2] row_mask:0xf bank_mask:0xf
	v_mul_f32_e32 v77, v77, v90
	s_nop 0
	v_add_f32_e32 v93, v93, v95
	s_nop 1
	v_mov_b32_dpp v95, v93 quad_perm:[2,3,0,1] row_mask:0xf bank_mask:0xf
	s_nop 0
	v_add_f32_e32 v93, v93, v95
	s_nop 1
	v_mov_b32_dpp v95, v93 row_half_mirror row_mask:0xf bank_mask:0xf
	s_nop 0
	v_add_f32_e32 v93, v93, v95
	s_nop 1
	v_mov_b32_dpp v95, v93 row_ror:8 row_mask:0xf bank_mask:0xf
	s_nop 0
	v_add_f32_e32 v93, v93, v95
	v_mov_b32_e32 v95, v93
	s_nop 1
	v_permlane16_swap_b32_e32 v95, v93
	s_nop 0
	v_add_f32_e32 v93, v93, v95
	v_fmamk_f32 v93, v93, 0x3c000000, v206
	v_cmp_gt_f32_e32 vcc, s36, v93
	v_mul_f32_e32 v95, 0x4f800000, v93
; __device__ __forceinline__ float shx(float v, int o, int lane) { return __int_as_float(__builtin_amdgcn_ds_bpermute((lane ^ o) << 2, __float_as_int(v))); }
; __device__ __forceinline__ int crow(int r, int hi) { return (r & 3) + 8 * (r >> 2) + 4 * hi; }
; __device__ __forceinline__ void attn_unit(LAS unsigned char* lds, bf16_t* Zg, const unsigned char* KVg, int S, int b, int h, int qb, const float* lq1, const float* lk1, const float* lq2, const float* lk2, const float* subln_g, const float* rel_bias, bool dostore = true) {
;     ...
;         for (int r = 0; r < 16; ++r) {
; #pragma unroll
;             for (int sft = 1; sft < 32; sft <<= 1) ss[r] += shx(ss[r], sft, lane);
;             ss[r] = (1.0f - LAMBDA_INIT) / sqrtf(ss[r] * (1.0f / 128.0f) + EPS); }
; #pragma unroll
;         for (int db = 0; db < 4; ++db) { const float sg = subln_g[db * 32 + r32];
; #pragma unroll
;             for (int r = 0; r < 16; ++r) exch[(32 * qsub + crow(r, hi)) * 128 + db * 32 + r32] = o[db][r] * ss[r] * sg; }
	s_nop 0
	v_cndmask_b32_e32 v93, v93, v95, vcc
	v_sqrt_f32_e32 v95, v93
	s_nop 0
	v_add_u32_e32 v96, -1, v95
	v_fma_f32 v97, -v96, v95, v93
	v_cmp_ge_f32_e64 s[4:5], 0, v97
	v_add_u32_e32 v97, 1, v95
	s_nop 0
	v_cndmask_b32_e64 v96, v95, v96, s[4:5]
	v_fma_f32 v95, -v97, v95, v93
	v_cmp_lt_f32_e64 s[4:5], 0, v95
	s_nop 1
	v_cndmask_b32_e64 v95, v96, v97, s[4:5]
	v_mul_f32_e32 v96, 0x37800000, v95
	v_cndmask_b32_e32 v95, v95, v96, vcc
	v_cmp_class_f32_e32 vcc, v93, v205
	s_nop 1
	v_cndmask_b32_e32 v93, v95, v93, vcc
	v_div_scale_f32 v95, s[4:5], v93, v93, s95
	v_rcp_f32_e32 v96, v95
	s_nop 0
	v_fma_f32 v97, -v95, v96, 1.0
	v_fmac_f32_e32 v96, v97, v96
	v_div_scale_f32 v97, vcc, s95, v93, s95
	v_mul_f32_e32 v98, v97, v96
	v_fma_f32 v99, -v95, v98, v97
	v_fmac_f32_e32 v98, v99, v96
	v_fma_f32 v95, -v95, v98, v97
	v_div_fmas_f32 v95, v95, v96, v98
	v_div_fixup_f32 v93, v95, v93, s95
	s_nop 1
	v_mov_b32_dpp v95, v94 quad_perm:[1,0,3,2] row_mask:0xf bank_mask:0xf
	v_mul_f32_e32 v70, v70, v93
	v_mul_f32_e32 v43, v43, v93
	s_nop 0
	v_add_f32_e32 v94, v94, v95
	s_nop 1
	v_mov_b32_dpp v95, v94 quad_perm:[2,3,0,1] row_mask:0xf bank_mask:0xf
	s_nop 0
	v_add_f32_e32 v94, v94, v95
	s_nop 1
	v_mov_b32_dpp v95, v94 row_half_mirror row_mask:0xf bank_mask:0xf
	s_nop 0
	v_add_f32_e32 v94, v94, v95
	s_nop 1
	v_mov_b32_dpp v95, v94 row_ror:8 row_mask:0xf bank_mask:0xf
	s_nop 0
	v_add_f32_e32 v94, v94, v95
	v_mov_b32_e32 v95, v94
	s_nop 1
	v_permlane16_swap_b32_e32 v95, v94
	s_nop 0
	v_add_f32_e32 v94, v94, v95
	v_fmamk_f32 v94, v94, 0x3c000000, v206
	v_cmp_gt_f32_e32 vcc, s36, v94
	v_mul_f32_e32 v95, 0x4f800000, v94
	s_nop 0
	v_cndmask_b32_e32 v94, v94, v95, vcc
	v_sqrt_f32_e32 v95, v94
	s_nop 0
	v_add_u32_e32 v96, -1, v95
	v_fma_f32 v97, -v96, v95, v94
	v_cmp_ge_f32_e64 s[4:5], 0, v97
	v_add_u32_e32 v97, 1, v95
	s_nop 0
	v_cndmask_b32_e64 v96, v95, v96, s[4:5]
	v_fma_f32 v95, -v97, v95, v94
	v_cmp_lt_f32_e64 s[4:5], 0, v95
	s_nop 1
	v_cndmask_b32_e64 v95, v96, v97, s[4:5]
	v_mul_f32_e32 v96, 0x37800000, v95
	v_cndmask_b32_e32 v95, v95, v96, vcc
	v_cmp_class_f32_e32 vcc, v94, v205
	s_nop 1
	v_cndmask_b32_e32 v94, v95, v94, vcc
	v_div_scale_f32 v95, s[4:5], v94, v94, s95
	v_rcp_f32_e32 v96, v95
	s_nop 0
	v_fma_f32 v97, -v95, v96, 1.0
	v_fmac_f32_e32 v96, v97, v96
	v_div_scale_f32 v97, vcc, s95, v94, s95
	v_mul_f32_e32 v98, v97, v96
	v_fma_f32 v99, -v95, v98, v97
	v_fmac_f32_e32 v98, v99, v96
	v_fma_f32 v95, -v95, v98, v97
	v_div_fmas_f32 v95, v95, v96, v98
	v_div_fixup_f32 v94, v95, v94, s95
	s_nop 1
	v_mov_b32_dpp v95, v92 quad_perm:[1,0,3,2] row_mask:0xf bank_mask:0xf
	v_mul_f32_e32 v71, v71, v94
	s_nop 0
	v_add_f32_e32 v92, v92, v95
	s_nop 1
	v_mov_b32_dpp v95, v92 quad_perm:[2,3,0,1] row_mask:0xf bank_mask:0xf
	s_nop 0
	v_add_f32_e32 v92, v92, v95
	s_nop 1
	v_mov_b32_dpp v95, v92 row_half_mirror row_mask:0xf bank_mask:0xf
	s_nop 0
	v_add_f32_e32 v92, v92, v95
	s_nop 1
	v_mov_b32_dpp v95, v92 row_ror:8 row_mask:0xf bank_mask:0xf
	s_nop 0
	v_add_f32_e32 v92, v92, v95
	v_mov_b32_e32 v95, v92
	s_nop 1
	v_permlane16_swap_b32_e32 v95, v92
	s_nop 0
	v_add_f32_e32 v92, v92, v95
	v_fmamk_f32 v92, v92, 0x3c000000, v206
	v_cmp_gt_f32_e32 vcc, s36, v92
	v_mul_f32_e32 v95, 0x4f800000, v92
	s_nop 0
	v_cndmask_b32_e32 v92, v92, v95, vcc
	v_sqrt_f32_e32 v95, v92
	s_nop 0
	v_add_u32_e32 v96, -1, v95
	v_fma_f32 v97, -v96, v95, v92
	v_cmp_ge_f32_e64 s[4:5], 0, v97
	v_add_u32_e32 v97, 1, v95
	s_nop 0
	v_cndmask_b32_e64 v96, v95, v96, s[4:5]
	v_fma_f32 v95, -v97, v95, v92
	v_cmp_lt_f32_e64 s[4:5], 0, v95
	s_nop 1
	v_cndmask_b32_e64 v95, v96, v97, s[4:5]
	v_mul_f32_e32 v96, 0x37800000, v95
	v_cndmask_b32_e32 v95, v95, v96, vcc
	v_cmp_class_f32_e32 vcc, v92, v205
	s_nop 1
	v_cndmask_b32_e32 v92, v95, v92, vcc
	v_div_scale_f32 v95, s[4:5], v92, v92, s95
	v_rcp_f32_e32 v96, v95
	s_nop 0
	v_fma_f32 v97, -v95, v96, 1.0
	v_fmac_f32_e32 v96, v97, v96
	v_div_scale_f32 v97, vcc, s95, v92, s95
	v_mul_f32_e32 v98, v97, v96
	v_fma_f32 v99, -v95, v98, v97
	v_fmac_f32_e32 v98, v99, v96
	v_fma_f32 v95, -v95, v98, v97
	v_div_fmas_f32 v95, v95, v96, v98
	v_div_fixup_f32 v92, v95, v92, s95
	s_nop 1
	v_mov_b32_dpp v95, v91 quad_perm:[1,0,3,2] row_mask:0xf bank_mask:0xf
	v_mul_f32_e32 v61, v61, v92
	s_nop 0
	v_add_f32_e32 v91, v91, v95
	s_nop 1
	v_mov_b32_dpp v95, v91 quad_perm:[2,3,0,1] row_mask:0xf bank_mask:0xf
	s_nop 0
	v_add_f32_e32 v91, v91, v95
	s_nop 1
	v_mov_b32_dpp v95, v91 row_half_mirror row_mask:0xf bank_mask:0xf
	s_nop 0
	v_add_f32_e32 v91, v91, v95
	s_nop 1
	v_mov_b32_dpp v95, v91 row_ror:8 row_mask:0xf bank_mask:0xf
	s_nop 0
	v_add_f32_e32 v91, v91, v95
	v_mov_b32_e32 v95, v91
	s_nop 1
	v_permlane16_swap_b32_e32 v95, v91
	s_nop 0
	v_add_f32_e32 v91, v91, v95
	v_fmamk_f32 v91, v91, 0x3c000000, v206
	v_cmp_gt_f32_e32 vcc, s36, v91
	v_mul_f32_e32 v95, 0x4f800000, v91
	s_nop 0
	v_cndmask_b32_e32 v91, v91, v95, vcc
	v_sqrt_f32_e32 v95, v91
	s_nop 0
	v_add_u32_e32 v96, -1, v95
	v_fma_f32 v97, -v96, v95, v91
	v_cmp_ge_f32_e64 s[4:5], 0, v97
	v_add_u32_e32 v97, 1, v95
	s_nop 0
	v_cndmask_b32_e64 v96, v95, v96, s[4:5]
	v_fma_f32 v95, -v97, v95, v91
	v_cmp_lt_f32_e64 s[4:5], 0, v95
	s_nop 1
	v_cndmask_b32_e64 v95, v96, v97, s[4:5]
	v_mul_f32_e32 v96, 0x37800000, v95
	v_cndmask_b32_e32 v95, v95, v96, vcc
	v_cmp_class_f32_e32 vcc, v91, v205
	s_nop 1
	v_cndmask_b32_e32 v91, v95, v91, vcc
	v_div_scale_f32 v95, s[4:5], v91, v91, s95
	v_rcp_f32_e32 v96, v95
	s_nop 0
	v_fma_f32 v97, -v95, v96, 1.0
	v_fmac_f32_e32 v96, v97, v96
	v_div_scale_f32 v97, vcc, s95, v91, s95
	v_mul_f32_e32 v98, v97, v96
	v_fma_f32 v99, -v95, v98, v97
	v_fmac_f32_e32 v98, v99, v96
	v_fma_f32 v95, -v95, v98, v97
; __device__ __forceinline__ float shx(float v, int o, int lane) { return __int_as_float(__builtin_amdgcn_ds_bpermute((lane ^ o) << 2, __float_as_int(v))); }
; __device__ __forceinline__ void attn_unit(LAS unsigned char* lds, bf16_t* Zg, const unsigned char* KVg, int S, int b, int h, int qb, const float* lq1, const float* lk1, const float* lq2, const float* lk2, const float* subln_g, const float* rel_bias, bool dostore = true) {
;     ...
;         for (int r = 0; r < 16; ++r) {
; #pragma unroll
;             for (int sft = 1; sft < 32; sft <<= 1) ss[r] += shx(ss[r], sft, lane);
;             ss[r] = (1.0f - LAMBDA_INIT) / sqrtf(ss[r] * (1.0f / 128.0f) + EPS); }
; #pragma unroll
;         for (int db = 0; db < 4; ++db) { const float sg = subln_g[db * 32 + r32];
	v_div_fmas_f32 v95, v95, v96, v98
	v_div_fixup_f32 v91, v95, v91, s95
	s_nop 1
	v_mov_b32_dpp v95, v89 quad_perm:[1,0,3,2] row_mask:0xf bank_mask:0xf
	v_mul_f32_e32 v72, v72, v91
	s_nop 0
	v_add_f32_e32 v89, v89, v95
	s_nop 1
	v_mov_b32_dpp v95, v89 quad_perm:[2,3,0,1] row_mask:0xf bank_mask:0xf
	s_nop 0
	v_add_f32_e32 v89, v89, v95
	s_nop 1
	v_mov_b32_dpp v95, v89 row_half_mirror row_mask:0xf bank_mask:0xf
	s_nop 0
	v_add_f32_e32 v89, v89, v95
	s_nop 1
	v_mov_b32_dpp v95, v89 row_ror:8 row_mask:0xf bank_mask:0xf
	s_nop 0
	v_add_f32_e32 v89, v89, v95
	v_mov_b32_e32 v95, v89
	s_nop 1
	v_permlane16_swap_b32_e32 v95, v89
	s_nop 0
	v_add_f32_e32 v89, v89, v95
	v_fmamk_f32 v89, v89, 0x3c000000, v206
	v_cmp_gt_f32_e32 vcc, s36, v89
	v_mul_f32_e32 v95, 0x4f800000, v89
	s_nop 0
	v_cndmask_b32_e32 v89, v89, v95, vcc
	v_sqrt_f32_e32 v95, v89
	s_nop 0
	v_add_u32_e32 v96, -1, v95
	v_fma_f32 v97, -v96, v95, v89
	v_cmp_ge_f32_e64 s[4:5], 0, v97
	v_add_u32_e32 v97, 1, v95
	s_nop 0
	v_cndmask_b32_e64 v96, v95, v96, s[4:5]
	v_fma_f32 v95, -v97, v95, v89
	v_cmp_lt_f32_e64 s[4:5], 0, v95
	s_nop 1
	v_cndmask_b32_e64 v95, v96, v97, s[4:5]
	v_mul_f32_e32 v96, 0x37800000, v95
	v_cndmask_b32_e32 v95, v95, v96, vcc
	v_cmp_class_f32_e32 vcc, v89, v205
	s_nop 1
	v_cndmask_b32_e32 v89, v95, v89, vcc
	v_div_scale_f32 v95, s[4:5], v89, v89, s95
	v_rcp_f32_e32 v96, v95
	s_nop 0
	v_fma_f32 v97, -v95, v96, 1.0
	v_fmac_f32_e32 v96, v97, v96
	v_div_scale_f32 v97, vcc, s95, v89, s95
	v_mul_f32_e32 v98, v97, v96
	v_fma_f32 v99, -v95, v98, v97
	v_fmac_f32_e32 v98, v99, v96
	v_fma_f32 v95, -v95, v98, v97
	v_div_fmas_f32 v95, v95, v96, v98
	v_div_fixup_f32 v89, v95, v89, s95
	s_nop 1
	v_mov_b32_dpp v95, v73 quad_perm:[1,0,3,2] row_mask:0xf bank_mask:0xf
	s_nop 1
	v_mov_b32_dpp v84, v68 quad_perm:[1,0,3,2] row_mask:0xf bank_mask:0xf
	v_mul_f32_e32 v63, v63, v89
	s_nop 0
	v_add_f32_e32 v73, v73, v95
	s_nop 1
	v_mov_b32_dpp v95, v73 quad_perm:[2,3,0,1] row_mask:0xf bank_mask:0xf
	s_nop 0
	v_add_f32_e32 v68, v68, v84
	s_nop 1
	v_mov_b32_dpp v84, v68 quad_perm:[2,3,0,1] row_mask:0xf bank_mask:0xf
	s_nop 0
	v_add_f32_e32 v73, v73, v95
	s_nop 1
	v_mov_b32_dpp v95, v73 row_half_mirror row_mask:0xf bank_mask:0xf
	s_nop 0
	v_add_f32_e32 v68, v68, v84
	s_nop 1
	v_mov_b32_dpp v84, v68 row_half_mirror row_mask:0xf bank_mask:0xf
	s_nop 0
	v_add_f32_e32 v73, v73, v95
	s_nop 1
	v_mov_b32_dpp v95, v73 row_ror:8 row_mask:0xf bank_mask:0xf
	s_nop 0
	v_add_f32_e32 v68, v68, v84
	s_nop 1
	v_mov_b32_dpp v84, v68 row_ror:8 row_mask:0xf bank_mask:0xf
	s_nop 0
	v_add_f32_e32 v73, v73, v95
	v_mov_b32_e32 v95, v73
	s_nop 1
	v_permlane16_swap_b32_e32 v95, v73
	s_nop 0
	v_add_f32_e32 v68, v68, v84
	v_mov_b32_e32 v84, v68
	s_nop 1
	v_permlane16_swap_b32_e32 v84, v68
	s_nop 0
	v_add_f32_e32 v73, v73, v95
	v_fmamk_f32 v73, v73, 0x3c000000, v206
	v_cmp_gt_f32_e32 vcc, s36, v73
	v_mul_f32_e32 v95, 0x4f800000, v73
	s_nop 0
	v_add_f32_e32 v68, v68, v84
	v_cndmask_b32_e32 v73, v73, v95, vcc
	v_sqrt_f32_e32 v95, v73
	v_fmamk_f32 v68, v68, 0x3c000000, v206
	v_mul_f32_e32 v84, 0x4f800000, v68
	v_add_u32_e32 v96, -1, v95
	v_fma_f32 v97, -v96, v95, v73
	v_cmp_ge_f32_e64 s[4:5], 0, v97
	v_add_u32_e32 v97, 1, v95
	s_nop 0
	v_cndmask_b32_e64 v96, v95, v96, s[4:5]
	v_fma_f32 v95, -v97, v95, v73
	v_cmp_lt_f32_e64 s[4:5], 0, v95
	s_nop 1
	v_cndmask_b32_e64 v95, v96, v97, s[4:5]
	v_mul_f32_e32 v96, 0x37800000, v95
	v_cndmask_b32_e32 v95, v95, v96, vcc
	v_cmp_class_f32_e32 vcc, v73, v205
	s_nop 1
	v_cndmask_b32_e32 v73, v95, v73, vcc
	v_div_scale_f32 v95, s[4:5], v73, v73, s95
	v_rcp_f32_e32 v96, v95
	s_nop 0
	v_fma_f32 v97, -v95, v96, 1.0
	v_fmac_f32_e32 v96, v97, v96
	v_div_scale_f32 v97, vcc, s95, v73, s95
	v_mul_f32_e32 v98, v97, v96
	v_fma_f32 v99, -v95, v98, v97
	v_fmac_f32_e32 v98, v99, v96
	v_fma_f32 v95, -v95, v98, v97
	v_div_fmas_f32 v95, v95, v96, v98
	v_cmp_gt_f32_e32 vcc, s36, v68
	v_div_fixup_f32 v73, v95, v73, s95
	v_mul_f32_e32 v64, v64, v73
	v_cndmask_b32_e32 v68, v68, v84, vcc
	v_sqrt_f32_e32 v84, v68
	s_nop 0
	v_add_u32_e32 v85, -1, v84
	v_fma_f32 v86, -v85, v84, v68
	v_cmp_ge_f32_e64 s[4:5], 0, v86
	v_add_u32_e32 v86, 1, v84
	s_nop 0
	v_cndmask_b32_e64 v85, v84, v85, s[4:5]
	v_fma_f32 v84, -v86, v84, v68
	v_cmp_lt_f32_e64 s[4:5], 0, v84
	s_nop 1
	v_cndmask_b32_e64 v84, v85, v86, s[4:5]
	v_mul_f32_e32 v85, 0x37800000, v84
	v_cndmask_b32_e32 v84, v84, v85, vcc
	v_cmp_class_f32_e32 vcc, v68, v205
	s_nop 1
	v_cndmask_b32_e32 v68, v84, v68, vcc
	v_div_scale_f32 v84, s[4:5], v68, v68, s95
	v_rcp_f32_e32 v85, v84
	s_nop 0
	v_fma_f32 v86, -v84, v85, 1.0
	v_fmac_f32_e32 v85, v86, v85
	v_div_scale_f32 v86, vcc, s95, v68, s95
	v_mul_f32_e32 v87, v86, v85
	v_fma_f32 v88, -v84, v87, v86
	v_fmac_f32_e32 v87, v88, v85
	v_fma_f32 v84, -v84, v87, v86
	v_div_fmas_f32 v84, v84, v85, v87
	v_div_fixup_f32 v68, v84, v68, s95
	global_load_dword v84, v82, s[68:69]
	global_load_dword v85, v82, s[68:69] offset:128
	global_load_dword v86, v82, s[68:69] offset:256
	global_load_dword v87, v82, s[68:69] offset:384
	v_mul_f32_e32 v65, v65, v68
	s_waitcnt vmcnt(0)
; __device__ __forceinline__ int crow(int r, int hi) { return (r & 3) + 8 * (r >> 2) + 4 * hi; }
; __device__ __forceinline__ void attn_unit(LAS unsigned char* lds, bf16_t* Zg, const unsigned char* KVg, int S, int b, int h, int qb, const float* lq1, const float* lk1, const float* lq2, const float* lk2, const float* subln_g, const float* rel_bias, bool dostore = true) {
;     ...
;         for (int db = 0; db < 4; ++db) { const float sg = subln_g[db * 32 + r32];
; #pragma unroll
;             for (int r = 0; r < 16; ++r) exch[(32 * qsub + crow(r, hi)) * 128 + db * 32 + r32] = o[db][r] * ss[r] * sg; }
	v_mul_f32_e32 v83, v83, v84
	v_mul_f32_e32 v78, v78, v84
	v_mul_f32_e32 v79, v79, v84
	v_mul_f32_e32 v80, v80, v84
	v_mul_f32_e32 v81, v81, v84
	v_mul_f32_e32 v74, v74, v84
	v_mul_f32_e32 v75, v75, v84
	v_mul_f32_e32 v76, v76, v84
	v_mul_f32_e32 v77, v77, v84
	v_mul_f32_e32 v70, v70, v84
	v_mul_f32_e32 v71, v71, v84
	v_mul_f32_e32 v61, v61, v84
	v_mul_f32_e32 v72, v72, v84
	v_mul_f32_e32 v63, v63, v84
	v_mul_f32_e32 v64, v84, v64
	v_mul_f32_e32 v65, v84, v65
	v_mul_f32_e32 v50, v50, v85
	ds_write2_b32 v0, v83, v50 offset1:32
	v_mul_f32_e32 v50, v51, v30
	v_mul_f32_e32 v50, v50, v85
	ds_write2_b32 v0, v78, v50 offset0:128 offset1:160
	v_mul_f32_e32 v50, v52, v44
	v_mul_f32_e32 v50, v50, v85
	ds_write2_b32 v18, v79, v50 offset1:32
	v_mul_f32_e32 v50, v53, v47
	v_mul_f32_e32 v50, v50, v85
	ds_write2_b32 v18, v80, v50 offset0:128 offset1:160
	v_mul_f32_e32 v50, v54, v62
	v_mul_f32_e32 v43, v43, v85
	v_mul_f32_e32 v50, v50, v85
	ds_write2_b32 v21, v70, v43 offset0:128 offset1:160
	v_mul_f32_e32 v43, v59, v94
	ds_write2_b32 v19, v81, v50 offset1:32
	v_mul_f32_e32 v50, v55, v66
	v_mul_f32_e32 v43, v43, v85
	v_mul_f32_e32 v50, v50, v85
	ds_write2_b32 v22, v71, v43 offset1:32
	v_mul_f32_e32 v43, v45, v92
	ds_write2_b32 v19, v74, v50 offset0:128 offset1:160
	v_mul_f32_e32 v50, v56, v67
	v_mul_f32_e32 v43, v43, v85
	v_mul_f32_e32 v50, v50, v85
	ds_write2_b32 v22, v61, v43 offset0:128 offset1:160
	v_mul_f32_e32 v43, v46, v91
	ds_write2_b32 v20, v75, v50 offset1:32
	v_mul_f32_e32 v50, v57, v69
	v_mul_f32_e32 v43, v43, v85
	v_mul_f32_e32 v50, v50, v85
	ds_write2_b32 v23, v72, v43 offset1:32
	v_mul_f32_e32 v43, v60, v89
	ds_write2_b32 v20, v76, v50 offset0:128 offset1:160
	v_mul_f32_e32 v50, v58, v90
	v_mul_f32_e32 v43, v43, v85
	v_mul_f32_e32 v50, v50, v85
	ds_write2_b32 v23, v63, v43 offset0:128 offset1:160
	v_mul_f32_e32 v43, v48, v73
	ds_write2_b32 v21, v77, v50 offset1:32
	v_mul_f32_e32 v43, v43, v85
	ds_write2_b32 v15, v64, v43 offset1:32
	v_mul_f32_e32 v43, v49, v68
	v_mul_f32_e32 v43, v43, v85
	ds_write2_b32 v15, v65, v43 offset0:128 offset1:160
	v_mul_f32_e32 v50, v34, v86
	v_mul_f32_e32 v34, v35, v30
	v_mul_f32_e32 v49, v34, v86
	v_mul_f32_e32 v34, v36, v44
	v_mul_f32_e32 v48, v34, v86
	v_mul_f32_e32 v34, v37, v47
	v_mul_f32_e32 v46, v34, v86
	v_mul_f32_e32 v34, v38, v62
	v_mul_f32_e32 v38, v25, v86
	v_mul_f32_e32 v25, v26, v90
	v_mul_f32_e32 v37, v25, v86
	v_mul_f32_e32 v25, v41, v93
	v_mul_f32_e32 v45, v34, v86
	v_mul_f32_e32 v34, v39, v66
	v_mul_f32_e32 v36, v25, v86
	v_mul_f32_e32 v25, v28, v94
	v_mul_f32_e32 v43, v34, v86
	v_mul_f32_e32 v34, v40, v67
	v_mul_f32_e32 v35, v25, v86
	v_mul_f32_e32 v25, v29, v92
	v_mul_f32_e32 v39, v34, v86
	v_mul_f32_e32 v34, v25, v86
	v_mul_f32_e32 v25, v42, v91
	v_mul_f32_e32 v29, v25, v86
	v_mul_f32_e32 v25, v31, v89
	v_mul_f32_e32 v28, v25, v86
	v_mul_f32_e32 v25, v32, v73
	v_mul_f32_e32 v26, v25, v86
	v_mul_f32_e32 v25, v33, v68
	v_mul_f32_e32 v25, v25, v86
	v_mul_f32_e32 v2, v2, v87
	ds_write2_b32 v0, v50, v2 offset0:64 offset1:96
	v_mul_f32_e32 v2, v3, v30
	v_mul_f32_e32 v2, v2, v87
	ds_write2_b32 v0, v49, v2 offset0:192 offset1:224
	v_mul_f32_e32 v0, v4, v44
	v_mul_f32_e32 v0, v0, v87
	ds_write2_b32 v18, v48, v0 offset0:64 offset1:96
	v_mul_f32_e32 v0, v5, v47
	v_mul_f32_e32 v0, v0, v87
	ds_write2_b32 v18, v46, v0 offset0:192 offset1:224
	v_mul_f32_e32 v0, v6, v62
	v_mul_f32_e32 v0, v0, v87
	ds_write2_b32 v19, v45, v0 offset0:64 offset1:96
	v_mul_f32_e32 v0, v7, v66
	v_mul_f32_e32 v0, v0, v87
	ds_write2_b32 v19, v43, v0 offset0:192 offset1:224
	v_mul_f32_e32 v0, v8, v67
	v_mul_f32_e32 v0, v0, v87
	ds_write2_b32 v20, v39, v0 offset0:64 offset1:96
	v_mul_f32_e32 v0, v9, v69
	v_mul_f32_e32 v0, v0, v87
	ds_write2_b32 v20, v38, v0 offset0:192 offset1:224
	v_mul_f32_e32 v0, v10, v90
	v_mul_f32_e32 v0, v0, v87
	ds_write2_b32 v21, v37, v0 offset0:64 offset1:96
	v_mul_f32_e32 v0, v11, v93
	v_mul_f32_e32 v0, v0, v87
	ds_write2_b32 v21, v36, v0 offset0:192 offset1:224
	v_mul_f32_e32 v0, v12, v94
	v_mul_f32_e32 v0, v0, v87
	ds_write2_b32 v22, v35, v0 offset0:64 offset1:96
	v_mul_f32_e32 v0, v13, v92
	v_mul_f32_e32 v0, v0, v87
	ds_write2_b32 v22, v34, v0 offset0:192 offset1:224
	v_mul_f32_e32 v0, v14, v91
	v_mul_f32_e32 v0, v0, v87
	ds_write2_b32 v23, v29, v0 offset0:64 offset1:96
	v_mul_f32_e32 v0, v24, v89
	v_mul_f32_e32 v0, v0, v87
	ds_write2_b32 v23, v28, v0 offset0:192 offset1:224
	v_mul_f32_e32 v0, v16, v73
	v_mul_f32_e32 v0, v0, v87
	ds_write2_b32 v15, v26, v0 offset0:64 offset1:96
	v_mul_f32_e32 v0, v17, v68
	v_mul_f32_e32 v0, v0, v87
	ds_write2_b32 v15, v25, v0 offset0:192 offset1:224
	s_branch .LBB0_187
